# pp_v7 + RC1 S0b log-decay prefix scan: eight DPP chains interleaved step by step (no s_nop pads, one exec toggle)
# speedup vs baseline: 1.0112x; 1.0046x over previous
.Lrc_hw:
	s_waitcnt vmcnt(4)
	v_mov_b64_e32 v[30:31], v[200:201]
	v_mov_b64_e32 v[32:33], v[202:203]
	v_mov_b64_e32 v[26:27], v[204:205]
	v_mov_b64_e32 v[28:29], v[206:207]
	v_mov_b64_e32 v[14:15], v[208:209]
	v_mov_b64_e32 v[16:17], v[210:211]
	v_mov_b64_e32 v[38:39], v[212:213]
	v_mov_b64_e32 v[40:41], v[214:215]
	v_mov_b64_e32 v[34:35], v[216:217]
	v_mov_b64_e32 v[36:37], v[218:219]
	v_mov_b64_e32 v[18:19], v[220:221]
	v_mov_b64_e32 v[20:21], v[222:223]
	v_mov_b64_e32 v[42:43], v[224:225]
	v_mov_b64_e32 v[44:45], v[226:227]
	s_lshl_b32 s0, s46, 8
	s_and_b32 s0, s0, 0x100
	s_add_i32 s47, s0, 0
	s_add_i32 s47, s47, 0x22500
	s_add_i32 s2, s47, s65
	v_add_f32_dpp v200, v6, v6 row_shr:1 row_mask:0xf bank_mask:0xf bound_ctrl:1
	v_add_f32_dpp v201, v7, v7 row_shr:1 row_mask:0xf bank_mask:0xf bound_ctrl:1
	v_add_f32_dpp v202, v8, v8 row_shr:1 row_mask:0xf bank_mask:0xf bound_ctrl:1
	v_add_f32_dpp v203, v9, v9 row_shr:1 row_mask:0xf bank_mask:0xf bound_ctrl:1
	v_add_f32_dpp v204, v2, v2 row_shr:1 row_mask:0xf bank_mask:0xf bound_ctrl:1
	v_add_f32_dpp v205, v3, v3 row_shr:1 row_mask:0xf bank_mask:0xf bound_ctrl:1
	v_add_f32_dpp v206, v4, v4 row_shr:1 row_mask:0xf bank_mask:0xf bound_ctrl:1
	v_add_f32_dpp v207, v5, v5 row_shr:1 row_mask:0xf bank_mask:0xf bound_ctrl:1
	v_add_f32_dpp v200, v200, v200 row_shr:2 row_mask:0xf bank_mask:0xf bound_ctrl:1
	v_add_f32_dpp v201, v201, v201 row_shr:2 row_mask:0xf bank_mask:0xf bound_ctrl:1
	v_add_f32_dpp v202, v202, v202 row_shr:2 row_mask:0xf bank_mask:0xf bound_ctrl:1
	v_add_f32_dpp v203, v203, v203 row_shr:2 row_mask:0xf bank_mask:0xf bound_ctrl:1
	v_add_f32_dpp v204, v204, v204 row_shr:2 row_mask:0xf bank_mask:0xf bound_ctrl:1
	v_add_f32_dpp v205, v205, v205 row_shr:2 row_mask:0xf bank_mask:0xf bound_ctrl:1
	v_add_f32_dpp v206, v206, v206 row_shr:2 row_mask:0xf bank_mask:0xf bound_ctrl:1
	v_add_f32_dpp v207, v207, v207 row_shr:2 row_mask:0xf bank_mask:0xf bound_ctrl:1
	v_add_f32_dpp v200, v200, v200 row_shr:4 row_mask:0xf bank_mask:0xf bound_ctrl:1
	v_add_f32_dpp v201, v201, v201 row_shr:4 row_mask:0xf bank_mask:0xf bound_ctrl:1
	v_add_f32_dpp v202, v202, v202 row_shr:4 row_mask:0xf bank_mask:0xf bound_ctrl:1
	v_add_f32_dpp v203, v203, v203 row_shr:4 row_mask:0xf bank_mask:0xf bound_ctrl:1
	v_add_f32_dpp v204, v204, v204 row_shr:4 row_mask:0xf bank_mask:0xf bound_ctrl:1
	v_add_f32_dpp v205, v205, v205 row_shr:4 row_mask:0xf bank_mask:0xf bound_ctrl:1
	v_add_f32_dpp v206, v206, v206 row_shr:4 row_mask:0xf bank_mask:0xf bound_ctrl:1
	v_add_f32_dpp v207, v207, v207 row_shr:4 row_mask:0xf bank_mask:0xf bound_ctrl:1
	v_add_f32_dpp v200, v200, v200 row_shr:8 row_mask:0xf bank_mask:0xf bound_ctrl:1
	v_add_f32_dpp v201, v201, v201 row_shr:8 row_mask:0xf bank_mask:0xf bound_ctrl:1
	v_add_f32_dpp v202, v202, v202 row_shr:8 row_mask:0xf bank_mask:0xf bound_ctrl:1
	v_add_f32_dpp v203, v203, v203 row_shr:8 row_mask:0xf bank_mask:0xf bound_ctrl:1
	v_add_f32_dpp v204, v204, v204 row_shr:8 row_mask:0xf bank_mask:0xf bound_ctrl:1
	v_add_f32_dpp v205, v205, v205 row_shr:8 row_mask:0xf bank_mask:0xf bound_ctrl:1
	v_add_f32_dpp v206, v206, v206 row_shr:8 row_mask:0xf bank_mask:0xf bound_ctrl:1
	v_add_f32_dpp v207, v207, v207 row_shr:8 row_mask:0xf bank_mask:0xf bound_ctrl:1
	v_mov_b32_e32 v208, v89
	v_mov_b32_e32 v209, v89
	v_mov_b32_e32 v210, v89
	v_mov_b32_e32 v211, v89
	v_mov_b32_e32 v212, v89
	v_mov_b32_e32 v213, v89
	v_mov_b32_e32 v214, v89
	v_mov_b32_e32 v215, v89
	v_mov_b32_dpp v208, v200 row_bcast:15 row_mask:0xa bank_mask:0xf
	v_mov_b32_dpp v209, v201 row_bcast:15 row_mask:0xa bank_mask:0xf
	v_mov_b32_dpp v210, v202 row_bcast:15 row_mask:0xa bank_mask:0xf
	v_mov_b32_dpp v211, v203 row_bcast:15 row_mask:0xa bank_mask:0xf
	v_mov_b32_dpp v212, v204 row_bcast:15 row_mask:0xa bank_mask:0xf
	v_mov_b32_dpp v213, v205 row_bcast:15 row_mask:0xa bank_mask:0xf
	v_mov_b32_dpp v214, v206 row_bcast:15 row_mask:0xa bank_mask:0xf
	v_mov_b32_dpp v215, v207 row_bcast:15 row_mask:0xa bank_mask:0xf
	v_add_f32_e32 v200, v200, v208
	v_add_f32_e32 v201, v201, v209
	v_add_f32_e32 v202, v202, v210
	v_add_f32_e32 v203, v203, v211
	v_add_f32_e32 v204, v204, v212
	v_add_f32_e32 v205, v205, v213
	v_add_f32_e32 v206, v206, v214
	v_add_f32_e32 v207, v207, v215
	v_mov_b32_e32 v208, v89
	v_mov_b32_e32 v209, v89
	v_mov_b32_e32 v210, v89
	v_mov_b32_e32 v211, v89
	v_mov_b32_e32 v212, v89
	v_mov_b32_e32 v213, v89
	v_mov_b32_e32 v214, v89
	v_mov_b32_e32 v215, v89
	v_mov_b32_dpp v208, v200 row_bcast:31 row_mask:0xc bank_mask:0xf
	v_mov_b32_dpp v209, v201 row_bcast:31 row_mask:0xc bank_mask:0xf
	v_mov_b32_dpp v210, v202 row_bcast:31 row_mask:0xc bank_mask:0xf
	v_mov_b32_dpp v211, v203 row_bcast:31 row_mask:0xc bank_mask:0xf
	v_mov_b32_dpp v212, v204 row_bcast:31 row_mask:0xc bank_mask:0xf
	v_mov_b32_dpp v213, v205 row_bcast:31 row_mask:0xc bank_mask:0xf
	v_mov_b32_dpp v214, v206 row_bcast:31 row_mask:0xc bank_mask:0xf
	v_mov_b32_dpp v215, v207 row_bcast:31 row_mask:0xc bank_mask:0xf
	v_add_f32_e32 v200, v200, v208
	v_add_f32_e32 v201, v201, v209
	v_add_f32_e32 v202, v202, v210
	v_add_f32_e32 v203, v203, v211
	v_add_f32_e32 v204, v204, v212
	v_add_f32_e32 v205, v205, v213
	v_add_f32_e32 v206, v206, v214
	v_add_f32_e32 v207, v207, v215
	ds_write_b32 v111, v200
	ds_write_b32 v111, v201 offset:4
	ds_write_b32 v111, v202 offset:8
	ds_write_b32 v111, v203 offset:12
	ds_write_b32 v111, v204 offset:16
	ds_write_b32 v111, v205 offset:20
	ds_write_b32 v111, v206 offset:24
	ds_write_b32 v111, v207 offset:28
	s_and_saveexec_b64 s[0:1], s[44:45]
	v_mov_b32_e32 v22, s2
	ds_write_b32 v22, v200
	ds_write_b32 v22, v201 offset:4
	ds_write_b32 v22, v202 offset:8
	ds_write_b32 v22, v203 offset:12
	ds_write_b32 v22, v204 offset:16
	ds_write_b32 v22, v205 offset:20
	ds_write_b32 v22, v206 offset:24
	ds_write_b32 v22, v207 offset:28
	s_or_b64 exec, exec, s[0:1]
	s_waitcnt vmcnt(3)
	v_and_b32_e32 v195, 0xffff0000, v30
	v_lshlrev_b32_e32 v194, 16, v30
	v_and_b32_e32 v199, 0xffff0000, v38
	v_lshlrev_b32_e32 v198, 16, v38
	s_waitcnt lgkmcnt(0)
	s_barrier
	ds_read_b128 v[82:85], v167
	ds_read_b128 v[54:57], v167 offset:16
	ds_read_b128 v[70:73], v167 offset:32
	ds_read_b128 v[50:53], v167 offset:48
	ds_read_b128 v[22:25], v167 offset:64
	ds_read_b128 v[78:81], v167 offset:96
	ds_read_b128 v[46:49], v167 offset:112
	ds_read_b128 v[74:77], v167 offset:128
	ds_read_b128 v[62:65], v167 offset:144
	ds_read_b128 v[66:69], v167 offset:160
	ds_read_b128 v[58:61], v167 offset:176
	v_pk_add_f32 v[198:199], v[198:199], v[194:195] neg_lo:[0,1] neg_hi:[0,1]
	s_waitcnt vmcnt(2)
	v_and_b32_e32 v197, 0xffff0000, v26
	v_lshlrev_b32_e32 v196, 16, v26
	s_waitcnt lgkmcnt(10)
	v_pk_fma_f32 v[82:83], v[198:199], v[82:83], v[194:195]
	v_and_b32_e32 v195, 0xffff0000, v34
	v_lshlrev_b32_e32 v194, 16, v34
	s_waitcnt vmcnt(0)
	v_and_b32_e32 v101, 0xffff0000, v42
	v_lshlrev_b32_e32 v100, 16, v42
	v_pk_add_f32 v[194:195], v[194:195], v[196:197] neg_lo:[0,1] neg_hi:[0,1]
	v_lshlrev_b32_e32 v30, 16, v27
	s_waitcnt lgkmcnt(8)
	v_pk_fma_f32 v[70:71], v[194:195], v[70:71], v[196:197]
	v_pk_add_f32 v[194:195], v[100:101], -1.0 op_sel_hi:[1,0]
	s_waitcnt lgkmcnt(5)
	v_mul_f32_e32 v78, v70, v78
	s_waitcnt lgkmcnt(3)
	v_pk_fma_f32 v[74:75], v[194:195], v[74:75], 1.0 op_sel_hi:[1,1,0]
	v_mul_f32_e32 v1, v71, v79
	v_pk_mul_f32 v[70:71], v[70:71], v[74:75]
	v_mul_f32_e32 v79, v1, v1
	v_pk_mul_f32 v[74:75], v[82:83], v[70:71]
	v_fmac_f32_e32 v79, v78, v78
	s_waitcnt lgkmcnt(1)
	v_pk_mul_f32 v[66:67], v[66:67], v[74:75]
	v_and_b32_e32 v75, 0xffff0000, v31
	v_add_f32_e32 v26, 0, v66
	v_add_f32_e32 v42, v67, v26
	v_lshlrev_b32_e32 v74, 16, v31
	v_and_b32_e32 v31, 0xffff0000, v27
	v_and_b32_e32 v27, 0xffff0000, v39
	v_lshlrev_b32_e32 v26, 16, v39
	v_pk_add_f32 v[26:27], v[26:27], v[74:75] neg_lo:[0,1] neg_hi:[0,1]
	v_and_b32_e32 v67, 0xffff0000, v43
	v_pk_fma_f32 v[38:39], v[26:27], v[84:85], v[74:75]
	v_and_b32_e32 v27, 0xffff0000, v35
	v_lshlrev_b32_e32 v26, 16, v35
	v_lshlrev_b32_e32 v66, 16, v43
	v_pk_add_f32 v[26:27], v[26:27], v[30:31] neg_lo:[0,1] neg_hi:[0,1]
	v_and_b32_e32 v43, 0xffff0000, v40
	v_pk_fma_f32 v[26:27], v[26:27], v[72:73], v[30:31]
	v_pk_add_f32 v[30:31], v[66:67], -1.0 op_sel_hi:[1,0]
	v_mul_f32_e32 v73, v26, v80
	v_pk_fma_f32 v[30:31], v[30:31], v[76:77], 1.0 op_sel_hi:[1,1,0]
	v_mul_f32_e32 v72, v27, v81
	v_pk_mul_f32 v[34:35], v[26:27], v[30:31]
	v_and_b32_e32 v31, 0xffff0000, v28
	v_pk_mul_f32 v[26:27], v[38:39], v[34:35]
	v_lshlrev_b32_e32 v30, 16, v28
	v_pk_mul_f32 v[26:27], v[68:69], v[26:27]
	v_and_b32_e32 v69, 0xffff0000, v44
	v_add_f32_e32 v26, v26, v42
	v_add_f32_e32 v74, v27, v26
	v_and_b32_e32 v27, 0xffff0000, v32
	v_lshlrev_b32_e32 v26, 16, v32
	v_lshlrev_b32_e32 v42, 16, v40
	v_pk_add_f32 v[42:43], v[42:43], v[26:27] neg_lo:[0,1] neg_hi:[0,1]
	v_lshlrev_b32_e32 v68, 16, v44
	v_pk_fma_f32 v[54:55], v[42:43], v[54:55], v[26:27]
	v_and_b32_e32 v27, 0xffff0000, v36
	v_lshlrev_b32_e32 v26, 16, v36
	v_pk_add_f32 v[26:27], v[26:27], v[30:31] neg_lo:[0,1] neg_hi:[0,1]
	v_lshlrev_b32_e32 v32, 16, v29
	v_pk_fma_f32 v[26:27], v[26:27], v[50:51], v[30:31]
	v_pk_add_f32 v[30:31], v[68:69], -1.0 op_sel_hi:[1,0]
	v_mul_f32_e32 v44, v26, v46
	v_pk_fma_f32 v[30:31], v[30:31], v[62:63], 1.0 op_sel_hi:[1,1,0]
	v_mul_f32_e32 v40, v27, v47
	v_pk_mul_f32 v[42:43], v[26:27], v[30:31]
	v_lshlrev_b32_e32 v28, 16, v41
	v_pk_mul_f32 v[26:27], v[54:55], v[42:43]
	v_and_b32_e32 v31, 0xffff0000, v45
	s_waitcnt lgkmcnt(0)
	v_pk_mul_f32 v[26:27], v[58:59], v[26:27]
	v_lshlrev_b32_e32 v30, 16, v45
	v_add_f32_e32 v26, v26, v74
	v_add_f32_e32 v36, v27, v26
	v_and_b32_e32 v27, 0xffff0000, v33
	v_lshlrev_b32_e32 v26, 16, v33
	v_and_b32_e32 v33, 0xffff0000, v29
	v_and_b32_e32 v29, 0xffff0000, v41
	v_pk_add_f32 v[28:29], v[28:29], v[26:27] neg_lo:[0,1] neg_hi:[0,1]
	v_fmac_f32_e32 v79, v73, v73
	v_pk_fma_f32 v[26:27], v[28:29], v[56:57], v[26:27]
	v_and_b32_e32 v29, 0xffff0000, v37
	v_lshlrev_b32_e32 v28, 16, v37
	v_pk_add_f32 v[28:29], v[28:29], v[32:33] neg_lo:[0,1] neg_hi:[0,1]
	v_fmac_f32_e32 v79, v72, v72
	v_pk_fma_f32 v[32:33], v[28:29], v[52:53], v[32:33]
	v_pk_add_f32 v[28:29], v[30:31], -1.0 op_sel_hi:[1,0]
	v_mul_f32_e32 v37, v32, v48
	v_pk_fma_f32 v[28:29], v[28:29], v[64:65], 1.0 op_sel_hi:[1,1,0]
	v_fmac_f32_e32 v79, v44, v44
	v_pk_mul_f32 v[28:29], v[32:33], v[28:29]
	v_fmac_f32_e32 v79, v40, v40
	v_pk_mul_f32 v[46:47], v[26:27], v[28:29]
	v_fmac_f32_e32 v79, v37, v37
	v_pk_mul_f32 v[46:47], v[60:61], v[46:47]
	v_lshl_add_u32 v88, v110, 2, s47
	v_add_f32_e32 v32, v46, v36
	v_add_f32_e32 v32, v47, v32
	ds_bpermute_b32 v41, v112, v32
	v_mul_f32_e32 v36, v33, v49
	v_fmac_f32_e32 v79, v36, v36
	ds_bpermute_b32 v33, v112, v79
	v_lshlrev_b32_e32 v58, 16, v18
	s_waitcnt lgkmcnt(1)
	v_add_f32_e32 v32, v32, v41
	ds_bpermute_b32 v45, v113, v32
	ds_read_b32 v41, v88
	ds_read_b128 v[48:51], v167 offset:80
	s_waitcnt lgkmcnt(3)
	v_add_f32_e32 v33, v79, v33
	ds_bpermute_b32 v47, v113, v33
	v_and_b32_e32 v59, 0xffff0000, v18
	s_waitcnt lgkmcnt(3)
	v_add_f32_e32 v32, v32, v45
	ds_bpermute_b32 v52, v114, v32
	v_lshlrev_b32_e32 v18, 16, v19
	s_waitcnt lgkmcnt(1)
	v_add_f32_e32 v53, v33, v47
	v_and_b32_e32 v33, 0xffff0000, v14
	v_and_b32_e32 v19, 0xffff0000, v19
	s_waitcnt lgkmcnt(0)
	v_add_f32_e32 v52, v32, v52
	v_lshlrev_b32_e32 v32, 16, v14
	v_lshlrev_b32_e32 v14, 16, v15
	v_and_b32_e32 v15, 0xffff0000, v15
	v_pk_add_f32 v[58:59], v[58:59], v[32:33] neg_lo:[0,1] neg_hi:[0,1]
	v_pk_add_f32 v[18:19], v[18:19], v[14:15] neg_lo:[0,1] neg_hi:[0,1]
	v_pk_fma_f32 v[32:33], v[58:59], v[22:23], v[32:33]
	v_pk_fma_f32 v[22:23], v[18:19], v[24:25], v[14:15]
	v_lshlrev_b32_e32 v14, 16, v16
	v_and_b32_e32 v15, 0xffff0000, v16
	v_lshlrev_b32_e32 v18, 16, v20
	v_and_b32_e32 v19, 0xffff0000, v20
	v_pk_add_f32 v[18:19], v[18:19], v[14:15] neg_lo:[0,1] neg_hi:[0,1]
	ds_read_b32 v45, v115
	ds_bpermute_b32 v56, v114, v53
	v_pk_fma_f32 v[18:19], v[18:19], v[48:49], v[14:15]
	v_lshlrev_b32_e32 v14, 16, v17
	v_and_b32_e32 v15, 0xffff0000, v17
	v_lshlrev_b32_e32 v16, 16, v21
	v_and_b32_e32 v17, 0xffff0000, v21
	v_pk_add_f32 v[16:17], v[16:17], v[14:15] neg_lo:[0,1] neg_hi:[0,1]
	v_pk_mul_f32 v[58:59], v[32:33], v[52:53] op_sel_hi:[1,0]
	v_pk_fma_f32 v[14:15], v[16:17], v[50:51], v[14:15]
	v_pk_mul_f32 v[24:25], v[22:23], v[52:53] op_sel_hi:[1,0]
	v_pk_mul_f32 v[60:61], v[18:19], v[52:53] op_sel_hi:[1,0]
	v_pk_mul_f32 v[16:17], v[14:15], v[52:53] op_sel_hi:[1,0]
	v_mov_b32_e32 v46, 0
	v_cvt_pk_bf16_f32 v48, v58, v59
	v_cvt_pk_bf16_f32 v49, v24, v25
	v_cvt_pk_bf16_f32 v50, v60, v61
	v_cvt_pk_bf16_f32 v51, v16, v17
	v_mov_b32_e32 v20, 0
	global_store_dwordx4 v[102:103], v[48:51], off
	s_and_saveexec_b64 s[0:1], s[4:5]
	s_cbranch_execz .LBB0_1055
	ds_read_b32 v16, v116
	s_waitcnt lgkmcnt(0)
	v_mul_f32_e32 v20, 0x3fb8aa3b, v16
